# v20 + up-GEMM epilogue: quieting v_max x,x fused into the relu v_max 0,x (97 VALU ops fewer per unit)
# baseline (speedup 1.0000x reference)
; __device__ __forceinline__ unsigned cvt_pk_bf16(float lo, float hi) { unsigned r; asm volatile("v_cvt_pk_bf16_f32 %0, %1, %2" : "=v"(r) : "v"(lo), "v"(hi)); return r; }
;     __device__ __forceinline__ void operator()(const f32x4 (&acc)[2][2][4][2], const Unit& u, int wr, int wc, int fr, int fq) const {
;     ...
;         for (int ai = 0; ai < 2; ++ai)
; #pragma unroll
;             for (int m = 0; m < 4; ++m) { bf16_t* rowp = O + (size_t)(row0 + ai * HALF + m * 16) * ldc + col0;
; #pragma unroll
;                 for (int bj = 0; bj < 2; ++bj) { f32x4 v0 = acc[ai][bj][m][0], v1 = acc[ai][bj][m][1];
;                     if (ROWSCALE) { v0 = v0 * rs[ai][m]; v1 = v1 * rs[ai][m]; }
;                     if (ACT == 2) {
; #pragma unroll
;                         for (int e = 0; e < 4; ++e) { const float a = fmaxf(v0[e], 0.f), b = fmaxf(v1[e], 0.f); v0[e] = a * a; v1[e] = b * b; } }
;                     u32x4 w; w.x = cvt_pk_bf16(v0[0], v0[1]); w.y = cvt_pk_bf16(v0[2], v0[3]); w.z = cvt_pk_bf16(v1[0], v1[1]); w.w = cvt_pk_bf16(v1[2], v1[3]);
;                     if (col0 + bj * CBS < ncols) *(u32x4*)(rowp + bj * CBS) = w; } }
.LBB0_1316:
	v_lshl_add_u32 v148, s8, 8, v1
	v_ashrrev_i32_e32 v149, 31, v148
	v_max_f32_e32 v122, 0, v122
	v_max_f32_e32 v123, 0, v123
	v_max_f32_e32 v124, 0, v124
	v_lshl_or_b32 v146, s36, 8, v153
	v_lshlrev_b64 v[150:151], 13, v[148:149]
	v_mul_f32_e32 v157, v122, v122
	v_max_f32_e32 v122, v127, v127
	v_mul_f32_e32 v127, v123, v123
	v_max_f32_e32 v123, v128, v128
	v_mul_f32_e32 v128, v124, v124
	v_ashrrev_i32_e32 v147, 31, v146
	v_lshl_add_u64 v[150:151], s[52:53], 0, v[150:151]
	v_max_f32_e32 v122, 0, v122
	v_max_f32_e32 v123, 0, v123
	v_max_f32_e32 v124, 0, v129
	v_max_f32_e32 v125, 0, v125
	v_lshl_add_u64 v[150:151], v[146:147], 1, v[150:151]
	v_max_f32_e32 v126, 0, v126
	v_mul_f32_e32 v122, v122, v122
	v_mul_f32_e32 v123, v123, v123
	v_mul_f32_e32 v124, v124, v124
	v_mul_f32_e32 v125, v125, v125
	v_cmp_gt_i32_e32 vcc, 2.0, v146
	v_mul_f32_e32 v126, v126, v126
	v_cvt_pk_bf16_f32 v122, v126, v122
	v_cvt_pk_bf16_f32 v123, v123, v124
	v_cvt_pk_bf16_f32 v124, v157, v127
	v_cvt_pk_bf16_f32 v125, v128, v125
	s_and_saveexec_b64 s[8:9], vcc
	s_cbranch_execz .LBB0_1318
	global_store_dwordx4 v[150:151], v[122:125], off
.LBB0_1318:
	s_or_b64 exec, exec, s[8:9]
	v_max_f32_e32 v114, 0, v114
	v_mul_f32_e32 v122, v114, v114
	v_max_f32_e32 v118, 0, v118
	v_max_f32_e32 v114, 0, v119
	v_max_f32_e32 v115, 0, v115
	v_max_f32_e32 v116, 0, v116
	v_mul_f32_e32 v118, v118, v118
	v_mul_f32_e32 v114, v114, v114
	v_mul_f32_e32 v119, v115, v115
	v_max_f32_e32 v115, v120, v120
	v_mul_f32_e32 v120, v116, v116
	v_max_f32_e32 v115, 0, v115
	v_max_f32_e32 v116, 0, v121
	v_max_f32_e32 v117, 0, v117
	v_cvt_pk_bf16_f32 v114, v118, v114
	v_or_b32_e32 v118, 32, v146
	v_mul_f32_e32 v115, v115, v115
	v_mul_f32_e32 v116, v116, v116
	v_mul_f32_e32 v117, v117, v117
	v_cmp_gt_i32_e64 s[8:9], 2.0, v118
	v_cvt_pk_bf16_f32 v115, v115, v116
	v_cvt_pk_bf16_f32 v116, v122, v119
	v_cvt_pk_bf16_f32 v117, v120, v117
	s_and_saveexec_b64 s[36:37], s[8:9]
	s_cbranch_execz .LBB0_1320
	global_store_dwordx4 v[150:151], v[114:117], off offset:64
.LBB0_1320:
	s_or_b64 exec, exec, s[36:37]
	s_nop 0
	v_or_b32_e32 v114, 16, v148
	v_ashrrev_i32_e32 v115, 31, v114
	v_max_f32_e32 v106, 0, v106
	v_max_f32_e32 v107, 0, v107
	v_max_f32_e32 v108, 0, v108
	v_lshlrev_b64 v[114:115], 13, v[114:115]
	v_mul_f32_e32 v116, v106, v106
	v_max_f32_e32 v106, v111, v111
	v_mul_f32_e32 v111, v107, v107
	v_max_f32_e32 v107, v112, v112
	v_mul_f32_e32 v112, v108, v108
	v_lshl_add_u64 v[114:115], s[52:53], 0, v[114:115]
	v_max_f32_e32 v106, 0, v106
	v_max_f32_e32 v107, 0, v107
	v_max_f32_e32 v108, 0, v113
	v_max_f32_e32 v109, 0, v109
	v_lshl_add_u64 v[114:115], v[146:147], 1, v[114:115]
	v_max_f32_e32 v110, 0, v110
	v_mul_f32_e32 v106, v106, v106
	v_mul_f32_e32 v107, v107, v107
	v_mul_f32_e32 v108, v108, v108
	v_mul_f32_e32 v109, v109, v109
	v_mul_f32_e32 v110, v110, v110
	v_cvt_pk_bf16_f32 v106, v110, v106
	v_cvt_pk_bf16_f32 v107, v107, v108
	v_cvt_pk_bf16_f32 v108, v116, v111
	v_cvt_pk_bf16_f32 v109, v112, v109
	s_and_saveexec_b64 s[36:37], vcc
	s_cbranch_execz .LBB0_1322
	global_store_dwordx4 v[114:115], v[106:109], off
.LBB0_1322:
	s_or_b64 exec, exec, s[36:37]
	v_max_f32_e32 v98, 0, v98
	v_max_f32_e32 v99, 0, v99
	v_max_f32_e32 v100, 0, v100
	v_mul_f32_e32 v106, v98, v98
	v_max_f32_e32 v98, v103, v103
	v_mul_f32_e32 v103, v99, v99
	v_max_f32_e32 v99, v104, v104
	v_mul_f32_e32 v104, v100, v100
	v_max_f32_e32 v98, 0, v98
	v_max_f32_e32 v99, 0, v99
	v_max_f32_e32 v100, 0, v105
	v_max_f32_e32 v101, 0, v101
	v_max_f32_e32 v102, 0, v102
	v_mul_f32_e32 v98, v98, v98
	v_mul_f32_e32 v99, v99, v99
	v_mul_f32_e32 v100, v100, v100
	v_mul_f32_e32 v101, v101, v101
	v_mul_f32_e32 v102, v102, v102
	v_cvt_pk_bf16_f32 v98, v102, v98
	v_cvt_pk_bf16_f32 v99, v99, v100
	v_cvt_pk_bf16_f32 v100, v106, v103
	v_cvt_pk_bf16_f32 v101, v104, v101
	s_and_saveexec_b64 s[36:37], s[8:9]
	s_cbranch_execz .LBB0_1324
	global_store_dwordx4 v[114:115], v[98:101], off offset:64
.LBB0_1324:
	s_or_b64 exec, exec, s[36:37]
	s_nop 0
	v_or_b32_e32 v98, 32, v148
	v_ashrrev_i32_e32 v99, 31, v98
	v_max_f32_e32 v90, 0, v90
	v_max_f32_e32 v91, 0, v91
	v_max_f32_e32 v92, 0, v92
	v_lshlrev_b64 v[98:99], 13, v[98:99]
	v_mul_f32_e32 v100, v90, v90
	v_max_f32_e32 v90, v95, v95
	v_mul_f32_e32 v95, v91, v91
	v_max_f32_e32 v91, v96, v96
	v_mul_f32_e32 v96, v92, v92
	v_lshl_add_u64 v[98:99], s[52:53], 0, v[98:99]
	v_max_f32_e32 v90, 0, v90
	v_max_f32_e32 v91, 0, v91
	v_max_f32_e32 v92, 0, v97
	v_max_f32_e32 v93, 0, v93
	v_lshl_add_u64 v[98:99], v[146:147], 1, v[98:99]
	v_max_f32_e32 v94, 0, v94
	v_mul_f32_e32 v90, v90, v90
	v_mul_f32_e32 v91, v91, v91
	v_mul_f32_e32 v92, v92, v92
	v_mul_f32_e32 v93, v93, v93
	v_mul_f32_e32 v94, v94, v94
	v_cvt_pk_bf16_f32 v90, v94, v90
	v_cvt_pk_bf16_f32 v91, v91, v92
	v_cvt_pk_bf16_f32 v92, v100, v95
	v_cvt_pk_bf16_f32 v93, v96, v93
	s_and_saveexec_b64 s[36:37], vcc
	s_cbranch_execz .LBB0_1326
	global_store_dwordx4 v[98:99], v[90:93], off
.LBB0_1326:
	s_or_b64 exec, exec, s[36:37]
	v_max_f32_e32 v82, 0, v82
	v_max_f32_e32 v83, 0, v83
	v_max_f32_e32 v84, 0, v84
	v_mul_f32_e32 v90, v82, v82
	v_max_f32_e32 v82, v87, v87
	v_mul_f32_e32 v87, v83, v83
	v_max_f32_e32 v83, v88, v88
	v_mul_f32_e32 v88, v84, v84
	v_max_f32_e32 v82, 0, v82
	v_max_f32_e32 v83, 0, v83
	v_max_f32_e32 v84, 0, v89
	v_max_f32_e32 v85, 0, v85
	v_max_f32_e32 v86, 0, v86
	v_mul_f32_e32 v82, v82, v82
	v_mul_f32_e32 v83, v83, v83
	v_mul_f32_e32 v84, v84, v84
	v_mul_f32_e32 v85, v85, v85
	v_mul_f32_e32 v86, v86, v86
	v_cvt_pk_bf16_f32 v82, v86, v82
	v_cvt_pk_bf16_f32 v83, v83, v84
	v_cvt_pk_bf16_f32 v84, v90, v87
	v_cvt_pk_bf16_f32 v85, v88, v85
	s_and_saveexec_b64 s[36:37], s[8:9]
	s_cbranch_execz .LBB0_1328
	global_store_dwordx4 v[98:99], v[82:85], off offset:64
; __device__ __forceinline__ unsigned cvt_pk_bf16(float lo, float hi) { unsigned r; asm volatile("v_cvt_pk_bf16_f32 %0, %1, %2" : "=v"(r) : "v"(lo), "v"(hi)); return r; }
;     __device__ __forceinline__ void operator()(const f32x4 (&acc)[2][2][4][2], const Unit& u, int wr, int wc, int fr, int fq) const {
;     ...
;         for (int ai = 0; ai < 2; ++ai)
; #pragma unroll
;             for (int m = 0; m < 4; ++m) { bf16_t* rowp = O + (size_t)(row0 + ai * HALF + m * 16) * ldc + col0;
; #pragma unroll
;                 for (int bj = 0; bj < 2; ++bj) { f32x4 v0 = acc[ai][bj][m][0], v1 = acc[ai][bj][m][1];
;                     if (ROWSCALE) { v0 = v0 * rs[ai][m]; v1 = v1 * rs[ai][m]; }
;                     if (ACT == 2) {
; #pragma unroll
;                         for (int e = 0; e < 4; ++e) { const float a = fmaxf(v0[e], 0.f), b = fmaxf(v1[e], 0.f); v0[e] = a * a; v1[e] = b * b; } }
;                     u32x4 w; w.x = cvt_pk_bf16(v0[0], v0[1]); w.y = cvt_pk_bf16(v0[2], v0[3]); w.z = cvt_pk_bf16(v1[0], v1[1]); w.w = cvt_pk_bf16(v1[2], v1[3]);
;                     if (col0 + bj * CBS < ncols) *(u32x4*)(rowp + bj * CBS) = w; } }
.LBB0_1328:
	s_or_b64 exec, exec, s[36:37]
	s_nop 0
	v_or_b32_e32 v82, 48, v148
	v_ashrrev_i32_e32 v83, 31, v82
	v_max_f32_e32 v74, 0, v74
	v_max_f32_e32 v75, 0, v75
	v_max_f32_e32 v76, 0, v76
	v_lshlrev_b64 v[82:83], 13, v[82:83]
	v_mul_f32_e32 v84, v74, v74
	v_max_f32_e32 v74, v79, v79
	v_mul_f32_e32 v79, v75, v75
	v_max_f32_e32 v75, v80, v80
	v_mul_f32_e32 v80, v76, v76
	v_lshl_add_u64 v[82:83], s[52:53], 0, v[82:83]
	v_max_f32_e32 v74, 0, v74
	v_max_f32_e32 v75, 0, v75
	v_max_f32_e32 v76, 0, v81
	v_max_f32_e32 v77, 0, v77
	v_lshl_add_u64 v[82:83], v[146:147], 1, v[82:83]
	v_max_f32_e32 v78, 0, v78
	v_mul_f32_e32 v74, v74, v74
	v_mul_f32_e32 v75, v75, v75
	v_mul_f32_e32 v76, v76, v76
	v_mul_f32_e32 v77, v77, v77
	v_mul_f32_e32 v78, v78, v78
	v_cvt_pk_bf16_f32 v74, v78, v74
	v_cvt_pk_bf16_f32 v75, v75, v76
	v_cvt_pk_bf16_f32 v76, v84, v79
	v_cvt_pk_bf16_f32 v77, v80, v77
	s_and_saveexec_b64 s[36:37], vcc
	s_cbranch_execz .LBB0_1330
	global_store_dwordx4 v[82:83], v[74:77], off
.LBB0_1330:
	s_or_b64 exec, exec, s[36:37]
	v_max_f32_e32 v66, 0, v66
	v_max_f32_e32 v67, 0, v67
	v_max_f32_e32 v68, 0, v68
	v_mul_f32_e32 v74, v66, v66
	v_max_f32_e32 v66, v71, v71
	v_mul_f32_e32 v71, v67, v67
	v_max_f32_e32 v67, v72, v72
	v_mul_f32_e32 v72, v68, v68
	v_max_f32_e32 v66, 0, v66
	v_max_f32_e32 v67, 0, v67
	v_max_f32_e32 v68, 0, v73
	v_max_f32_e32 v69, 0, v69
	v_max_f32_e32 v70, 0, v70
	v_mul_f32_e32 v66, v66, v66
	v_mul_f32_e32 v67, v67, v67
	v_mul_f32_e32 v68, v68, v68
	v_mul_f32_e32 v69, v69, v69
	v_mul_f32_e32 v70, v70, v70
	v_cvt_pk_bf16_f32 v66, v70, v66
	v_cvt_pk_bf16_f32 v67, v67, v68
	v_cvt_pk_bf16_f32 v68, v74, v71
	v_cvt_pk_bf16_f32 v69, v72, v69
	s_and_saveexec_b64 s[36:37], s[8:9]
	s_cbranch_execz .LBB0_1332
	global_store_dwordx4 v[82:83], v[66:69], off offset:64
.LBB0_1332:
	s_or_b64 exec, exec, s[36:37]
	v_lshlrev_b64 v[66:67], 13, v[148:149]
	v_max_f32_e32 v58, 0, v58
	v_max_f32_e32 v59, 0, v59
	v_max_f32_e32 v60, 0, v60
	v_lshl_add_u64 v[66:67], s[52:53], 0, v[66:67]
	v_mul_f32_e32 v68, v58, v58
	v_max_f32_e32 v58, v63, v63
	v_mul_f32_e32 v63, v59, v59
	v_max_f32_e32 v59, v64, v64
	v_mul_f32_e32 v64, v60, v60
	v_lshl_add_u64 v[66:67], v[146:147], 1, v[66:67]
	v_max_f32_e32 v58, 0, v58
	v_max_f32_e32 v59, 0, v59
	v_max_f32_e32 v60, 0, v65
	v_max_f32_e32 v61, 0, v61
	v_lshl_add_u64 v[66:67], v[66:67], 0, s[16:17]
	v_max_f32_e32 v62, 0, v62
	v_mul_f32_e32 v58, v58, v58
	v_mul_f32_e32 v59, v59, v59
	v_mul_f32_e32 v60, v60, v60
	v_mul_f32_e32 v61, v61, v61
	v_mul_f32_e32 v62, v62, v62
	v_cvt_pk_bf16_f32 v58, v62, v58
	v_cvt_pk_bf16_f32 v59, v59, v60
	v_cvt_pk_bf16_f32 v60, v68, v63
	v_cvt_pk_bf16_f32 v61, v64, v61
	s_and_saveexec_b64 s[36:37], vcc
	s_cbranch_execz .LBB0_1334
	global_store_dwordx4 v[66:67], v[58:61], off
.LBB0_1334:
	s_or_b64 exec, exec, s[36:37]
	v_max_f32_e32 v50, 0, v50
	v_max_f32_e32 v51, 0, v51
	v_max_f32_e32 v52, 0, v52
	v_mul_f32_e32 v58, v50, v50
	v_max_f32_e32 v50, v55, v55
	v_mul_f32_e32 v55, v51, v51
	v_max_f32_e32 v51, v56, v56
	v_mul_f32_e32 v56, v52, v52
	v_max_f32_e32 v50, 0, v50
	v_max_f32_e32 v51, 0, v51
	v_max_f32_e32 v52, 0, v57
	v_max_f32_e32 v53, 0, v53
	v_max_f32_e32 v54, 0, v54
	v_mul_f32_e32 v50, v50, v50
	v_mul_f32_e32 v51, v51, v51
	v_mul_f32_e32 v52, v52, v52
	v_mul_f32_e32 v53, v53, v53
	v_mul_f32_e32 v54, v54, v54
	v_cvt_pk_bf16_f32 v50, v54, v50
	v_cvt_pk_bf16_f32 v51, v51, v52
	v_cvt_pk_bf16_f32 v52, v58, v55
	v_cvt_pk_bf16_f32 v53, v56, v53
	s_and_saveexec_b64 s[36:37], s[8:9]
	s_cbranch_execz .LBB0_1336
	global_store_dwordx4 v[66:67], v[50:53], off offset:64
.LBB0_1336:
	s_or_b64 exec, exec, s[36:37]
	v_lshlrev_b64 v[50:51], 13, v[148:149]
	v_max_f32_e32 v42, 0, v42
	v_max_f32_e32 v43, 0, v43
	v_max_f32_e32 v44, 0, v44
	v_lshl_add_u64 v[50:51], s[52:53], 0, v[50:51]
	v_mul_f32_e32 v52, v42, v42
	v_max_f32_e32 v42, v47, v47
	v_mul_f32_e32 v47, v43, v43
	v_max_f32_e32 v43, v48, v48
	v_mul_f32_e32 v48, v44, v44
	v_lshl_add_u64 v[50:51], v[146:147], 1, v[50:51]
	v_max_f32_e32 v42, 0, v42
	v_max_f32_e32 v43, 0, v43
	v_max_f32_e32 v44, 0, v49
	v_max_f32_e32 v45, 0, v45
	v_lshl_add_u64 v[50:51], v[50:51], 0, s[18:19]
	v_max_f32_e32 v46, 0, v46
	v_mul_f32_e32 v42, v42, v42
	v_mul_f32_e32 v43, v43, v43
	v_mul_f32_e32 v44, v44, v44
	v_mul_f32_e32 v45, v45, v45
	v_mul_f32_e32 v46, v46, v46
	v_cvt_pk_bf16_f32 v42, v46, v42
	v_cvt_pk_bf16_f32 v43, v43, v44
	v_cvt_pk_bf16_f32 v44, v52, v47
	v_cvt_pk_bf16_f32 v45, v48, v45
	s_and_saveexec_b64 s[36:37], vcc
	s_cbranch_execz .LBB0_1338
	global_store_dwordx4 v[50:51], v[42:45], off
; __device__ __forceinline__ unsigned cvt_pk_bf16(float lo, float hi) { unsigned r; asm volatile("v_cvt_pk_bf16_f32 %0, %1, %2" : "=v"(r) : "v"(lo), "v"(hi)); return r; }
;     __device__ __forceinline__ void operator()(const f32x4 (&acc)[2][2][4][2], const Unit& u, int wr, int wc, int fr, int fq) const {
;     ...
;         for (int ai = 0; ai < 2; ++ai)
; #pragma unroll
;             for (int m = 0; m < 4; ++m) { bf16_t* rowp = O + (size_t)(row0 + ai * HALF + m * 16) * ldc + col0;
; #pragma unroll
;                 for (int bj = 0; bj < 2; ++bj) { f32x4 v0 = acc[ai][bj][m][0], v1 = acc[ai][bj][m][1];
;                     if (ROWSCALE) { v0 = v0 * rs[ai][m]; v1 = v1 * rs[ai][m]; }
;                     if (ACT == 2) {
; #pragma unroll
;                         for (int e = 0; e < 4; ++e) { const float a = fmaxf(v0[e], 0.f), b = fmaxf(v1[e], 0.f); v0[e] = a * a; v1[e] = b * b; } }
;                     u32x4 w; w.x = cvt_pk_bf16(v0[0], v0[1]); w.y = cvt_pk_bf16(v0[2], v0[3]); w.z = cvt_pk_bf16(v1[0], v1[1]); w.w = cvt_pk_bf16(v1[2], v1[3]);
;                     if (col0 + bj * CBS < ncols) *(u32x4*)(rowp + bj * CBS) = w; } }
.LBB0_1338:
	s_or_b64 exec, exec, s[36:37]
	v_max_f32_e32 v34, 0, v34
	v_max_f32_e32 v35, 0, v35
	v_max_f32_e32 v36, 0, v36
	v_mul_f32_e32 v42, v34, v34
	v_max_f32_e32 v34, v39, v39
	v_mul_f32_e32 v39, v35, v35
	v_max_f32_e32 v35, v40, v40
	v_mul_f32_e32 v40, v36, v36
	v_max_f32_e32 v34, 0, v34
	v_max_f32_e32 v35, 0, v35
	v_max_f32_e32 v36, 0, v41
	v_max_f32_e32 v37, 0, v37
	v_max_f32_e32 v38, 0, v38
	v_mul_f32_e32 v34, v34, v34
	v_mul_f32_e32 v35, v35, v35
	v_mul_f32_e32 v36, v36, v36
	v_mul_f32_e32 v37, v37, v37
	v_mul_f32_e32 v38, v38, v38
	v_cvt_pk_bf16_f32 v34, v38, v34
	v_cvt_pk_bf16_f32 v35, v35, v36
	v_cvt_pk_bf16_f32 v36, v42, v39
	v_cvt_pk_bf16_f32 v37, v40, v37
	s_and_saveexec_b64 s[36:37], s[8:9]
	s_cbranch_execz .LBB0_1340
	global_store_dwordx4 v[50:51], v[34:37], off offset:64
.LBB0_1340:
	s_or_b64 exec, exec, s[36:37]
	v_lshlrev_b64 v[34:35], 13, v[148:149]
	v_max_f32_e32 v26, 0, v26
	v_max_f32_e32 v27, 0, v27
	v_max_f32_e32 v28, 0, v28
	v_lshl_add_u64 v[34:35], s[52:53], 0, v[34:35]
	v_mul_f32_e32 v36, v26, v26
	v_max_f32_e32 v26, v31, v31
	v_mul_f32_e32 v31, v27, v27
	v_max_f32_e32 v27, v32, v32
	v_mul_f32_e32 v32, v28, v28
	v_lshl_add_u64 v[34:35], v[146:147], 1, v[34:35]
	v_max_f32_e32 v26, 0, v26
	v_max_f32_e32 v27, 0, v27
	v_max_f32_e32 v28, 0, v33
	v_max_f32_e32 v29, 0, v29
	v_lshl_add_u64 v[34:35], v[34:35], 0, s[20:21]
	v_max_f32_e32 v30, 0, v30
	v_mul_f32_e32 v26, v26, v26
	v_mul_f32_e32 v27, v27, v27
	v_mul_f32_e32 v28, v28, v28
	v_mul_f32_e32 v29, v29, v29
	v_mul_f32_e32 v30, v30, v30
	v_cvt_pk_bf16_f32 v26, v30, v26
	v_cvt_pk_bf16_f32 v27, v27, v28
	v_cvt_pk_bf16_f32 v28, v36, v31
	v_cvt_pk_bf16_f32 v29, v32, v29
	s_and_saveexec_b64 s[36:37], vcc
	s_cbranch_execz .LBB0_1342
	global_store_dwordx4 v[34:35], v[26:29], off
.LBB0_1342:
	s_or_b64 exec, exec, s[36:37]
	v_max_f32_e32 v18, 0, v18
	v_max_f32_e32 v19, 0, v19
	v_max_f32_e32 v20, 0, v20
	v_mul_f32_e32 v26, v18, v18
	v_max_f32_e32 v18, v23, v23
	v_mul_f32_e32 v23, v19, v19
	v_max_f32_e32 v19, v24, v24
	v_mul_f32_e32 v24, v20, v20
	v_max_f32_e32 v18, 0, v18
	v_max_f32_e32 v19, 0, v19
	v_max_f32_e32 v20, 0, v25
	v_max_f32_e32 v21, 0, v21
	v_max_f32_e32 v22, 0, v22
	v_mul_f32_e32 v18, v18, v18
	v_mul_f32_e32 v19, v19, v19
	v_mul_f32_e32 v20, v20, v20
	v_mul_f32_e32 v21, v21, v21
	v_mul_f32_e32 v22, v22, v22
	v_cvt_pk_bf16_f32 v18, v22, v18
	v_cvt_pk_bf16_f32 v19, v19, v20
	v_cvt_pk_bf16_f32 v20, v26, v23
	v_cvt_pk_bf16_f32 v21, v24, v21
	s_and_saveexec_b64 s[36:37], s[8:9]
	s_cbranch_execz .LBB0_1344
	global_store_dwordx4 v[34:35], v[18:21], off offset:64
.LBB0_1344:
	s_or_b64 exec, exec, s[36:37]
	v_lshlrev_b64 v[18:19], 13, v[148:149]
	v_max_f32_e32 v10, 0, v10
	v_max_f32_e32 v11, 0, v11
	v_max_f32_e32 v12, 0, v12
	v_lshl_add_u64 v[18:19], s[52:53], 0, v[18:19]
	v_mul_f32_e32 v20, v10, v10
	v_max_f32_e32 v10, v15, v15
	v_mul_f32_e32 v15, v11, v11
	v_max_f32_e32 v11, v16, v16
	v_mul_f32_e32 v16, v12, v12
	v_lshl_add_u64 v[18:19], v[146:147], 1, v[18:19]
	v_max_f32_e32 v10, 0, v10
	v_max_f32_e32 v11, 0, v11
	v_max_f32_e32 v12, 0, v17
	v_max_f32_e32 v13, 0, v13
	v_lshl_add_u64 v[18:19], v[18:19], 0, s[22:23]
	v_max_f32_e32 v14, 0, v14
	v_mul_f32_e32 v10, v10, v10
	v_mul_f32_e32 v11, v11, v11
	v_mul_f32_e32 v12, v12, v12
	v_mul_f32_e32 v13, v13, v13
	v_mul_f32_e32 v14, v14, v14
	v_cvt_pk_bf16_f32 v10, v14, v10
	v_cvt_pk_bf16_f32 v11, v11, v12
	v_cvt_pk_bf16_f32 v12, v20, v15
	v_cvt_pk_bf16_f32 v13, v16, v13
	s_and_saveexec_b64 s[36:37], vcc
	s_cbranch_execz .LBB0_1346
	global_store_dwordx4 v[18:19], v[10:13], off
.LBB0_1346:
	s_or_b64 exec, exec, s[36:37]
	v_max_f32_e32 v2, 0, v2
	v_max_f32_e32 v3, 0, v3
	v_max_f32_e32 v4, 0, v4
	v_mul_f32_e32 v10, v2, v2
	v_max_f32_e32 v2, v7, v7
	v_mul_f32_e32 v7, v3, v3
	v_max_f32_e32 v3, v8, v8
	v_mul_f32_e32 v8, v4, v4
	v_max_f32_e32 v2, 0, v2
	v_max_f32_e32 v3, 0, v3
	v_max_f32_e32 v4, 0, v9
	v_max_f32_e32 v5, 0, v5
	v_max_f32_e32 v6, 0, v6
	v_mul_f32_e32 v2, v2, v2
	v_mul_f32_e32 v3, v3, v3
	v_mul_f32_e32 v4, v4, v4
	v_mul_f32_e32 v5, v5, v5
	v_mul_f32_e32 v6, v6, v6
	v_cvt_pk_bf16_f32 v2, v6, v2
	v_cvt_pk_bf16_f32 v3, v3, v4
	v_cvt_pk_bf16_f32 v4, v10, v7
	v_cvt_pk_bf16_f32 v5, v8, v5
	s_and_saveexec_b64 s[36:37], s[8:9]
	s_cbranch_execz .LBB0_1348
	global_store_dwordx4 v[18:19], v[2:5], off offset:64
